# grid barrier: XCD leader adds to TOP and every workgroup polls TOP directly (no TOPGEN/XGEN hops)
# speedup vs baseline: 1.0085x; 1.0040x over previous
.LBB0_592:
	v_readlane_b32 s0, v252, 56
	v_readlane_b32 s1, v252, 57
	v_cvt_f32_u32_e32 v0, v3
	v_sub_u32_e32 v5, 0, v3
	v_rcp_iflag_f32_e32 v0, v0
	s_nop 1
	global_atomic_add v4, v1, v211, s[0:1] sc0
	v_mul_f32_e32 v0, 0x4f7ffffe, v0
	v_cvt_u32_f32_e32 v0, v0
	v_mul_lo_u32 v5, v5, v0
	v_mul_hi_u32 v5, v0, v5
	v_add_u32_e32 v0, v0, v5
	s_waitcnt vmcnt(0)
	v_mul_hi_u32 v0, v4, v0
	v_mul_lo_u32 v5, v0, v3
	v_sub_u32_e32 v5, v4, v5
	v_add_u32_e32 v6, 1, v0
	v_cmp_ge_u32_e32 vcc, v5, v3
	v_add_u32_e32 v4, 1, v4
	s_nop 0
	v_cndmask_b32_e32 v0, v0, v6, vcc
	v_sub_u32_e32 v6, v5, v3
	v_cndmask_b32_e32 v5, v5, v6, vcc
	v_add_u32_e32 v6, 1, v0
	v_cmp_ge_u32_e32 vcc, v5, v3
	s_nop 1
	v_cndmask_b32_e32 v0, v0, v6, vcc
	v_mul_lo_u32 v5, v3, v0
	v_add_u32_e32 v3, v5, v3
	v_cmp_ne_u32_e32 vcc, v4, v3
	s_waitcnt lgkmcnt(0)
	v_add_u32_e32 v0, 1, v0
	v_mul_lo_u32 v0, v0, v2
	v_readlane_b32 s0, v252, 60
	v_readlane_b32 s1, v252, 61
	s_cbranch_vccnz .Lxb_poll
	buffer_wbl2 sc1
	s_waitcnt vmcnt(0)
	global_atomic_add v1, v211, s[0:1]
.Lxb_poll:
	s_mov_b32 s8, 0
	s_nop 4
.Lxb_spin:
	global_load_dword v3, v1, s[0:1] sc1
	s_waitcnt vmcnt(0)
	v_sub_u32_e32 v3, v3, v0
	v_cmp_gt_i32_e32 vcc, 0, v3
	s_cbranch_vccz .Lxb_done
	s_sleep 0
	s_add_u32 s8, s8, 1
	s_cmp_lt_u32 s8, 0x200000
	s_cbranch_scc1 .Lxb_spin
.Lxb_done:
	buffer_inv sc1
	s_waitcnt vmcnt(0)
	s_branch .LBB0_22
